# speedup vs baseline: 1.0156x; 1.0016x over previous
; DI float rs_of(const float* ss, int row) { return 1.0f / sqrtf(ss[row] * (1.0f / DM) + EPS); }
;     DI void operator()(AccRef acc, const Unit& u, int wr, int wc, int fr, int fq) const {
;     ...
;             const bool isv = pn >= 8; const int c0 = (pn - (isv ? 8 : 4)) * 256 + cc0;
;             const bool f32out = smp || ((pm & 15) >= 14);
;             float* fo = out + (smp ? (isv ? O_AVS : O_AKS) : (isv ? O_AVP : O_AKP));
; #pragma unroll
;             for (int ai = 0; ai < 2; ++ai)
; #pragma unroll
;                 for (int m = 0; m < 4; ++m) {
;                     const int rl = rl0 + ai * 128 + m * 16; const float r = rs_of(ss, pm * 256 + rl);
;                     int b, s; if (smp) { b = rl >> 5; s = rl & 31; } else { b = pm >> 4; s = (pm & 15) * 256 + rl; }
;                     if (f32out) { const size_t orow = smp ? (size_t)rl : (size_t)b * 512 + (s - 3584);
.LBB0_537:
	s_andn2_b64 vcc, exec, s[10:11]
	s_cbranch_vccnz .LBB0_683
	s_cmp_lt_u32 s58, 8
	s_cselect_b64 s[14:15], -1, 0
	s_cmp_gt_u32 s58, 7
	s_mov_b32 s1, 0x4480000
	s_cselect_b32 s0, -8, -4
	s_cselect_b32 s4, s1, 0x4080000
	s_mov_b32 s1, 0x5ac0000
	s_cselect_b32 s5, s1, 0x5a80000
	s_add_i32 s0, s0, s58
	s_and_b32 s10, s56, 15
	s_cmp_gt_u32 s10, 13
	v_lshl_add_u32 v150, s0, 8, v146
	s_cselect_b64 s[0:1], -1, 0
	s_or_b64 s[64:65], s[12:13], s[0:1]
	s_and_b64 s[0:1], s[12:13], exec
	s_cselect_b32 s0, s5, s4
	s_lshl_b32 s0, s0, 2
	s_add_u32 s0, s20, s0
	s_addc_u32 s1, s21, 0
	s_lshl_b32 s49, s56, 8
	v_add_u32_e32 v154, s49, v148
	v_ashrrev_i32_e32 v155, 31, v154
	v_lshl_add_u64 v[154:155], v[154:155], 2, s[38:39]
	v_mov_b64_e32 v[240:241], v[154:155]
	v_mov_b32_e32 v235, 0
	global_load_dword v192, v[240:241], off
	v_mov_b32_e32 v234, 0x40
	v_lshl_add_u64 v[240:241], v[240:241], 0, v[234:235]
	global_load_dword v215, v[240:241], off
	v_mov_b32_e32 v234, 0x40
	v_lshl_add_u64 v[240:241], v[240:241], 0, v[234:235]
	global_load_dword v236, v[240:241], off
	v_mov_b32_e32 v234, 0x40
	v_lshl_add_u64 v[240:241], v[240:241], 0, v[234:235]
	global_load_dword v237, v[240:241], off
	v_mov_b32_e32 v234, 0x140
	v_lshl_add_u64 v[240:241], v[240:241], 0, v[234:235]
	global_load_dword v238, v[240:241], off
	v_mov_b32_e32 v234, 0x40
	v_lshl_add_u64 v[240:241], v[240:241], 0, v[234:235]
	global_load_dword v239, v[240:241], off
	v_mov_b32_e32 v234, 0x40
	v_lshl_add_u64 v[240:241], v[240:241], 0, v[234:235]
	global_load_dword v232, v[240:241], off
	v_mov_b32_e32 v234, 0x40
	v_lshl_add_u64 v[240:241], v[240:241], 0, v[234:235]
	global_load_dword v233, v[240:241], off
	s_waitcnt vmcnt(0)
	v_mov_b32_e32 v147, v192
	s_lshl_b32 s60, s10, 8
	v_ashrrev_i32_e32 v151, 31, v150
	v_lshl_add_u64 v[152:153], v[150:151], 2, s[0:1]
	s_ashr_i32 s62, s56, 4
	v_fmamk_f32 v147, v147, 0x3a000000, v167
	v_cmp_gt_f32_e32 vcc, s88, v147
	v_mul_f32_e32 v149, 0x4f800000, v147
	s_nop 0
	v_cndmask_b32_e32 v147, v147, v149, vcc
	v_sqrt_f32_e32 v149, v147
	s_nop 0
	v_add_u32_e32 v154, -1, v149
	v_fma_f32 v155, -v154, v149, v147
	v_cmp_ge_f32_e64 s[10:11], 0, v155
	v_add_u32_e32 v155, 1, v149
	s_nop 0
	v_cndmask_b32_e64 v154, v149, v154, s[10:11]
	v_fma_f32 v149, -v155, v149, v147
	v_cmp_lt_f32_e64 s[10:11], 0, v149
	s_nop 1
	v_cndmask_b32_e64 v149, v154, v155, s[10:11]
	v_mul_f32_e32 v154, 0x37800000, v149
	v_cndmask_b32_e32 v149, v149, v154, vcc
	v_cmp_class_f32_e32 vcc, v147, v168
	s_nop 1
	v_cndmask_b32_e32 v147, v149, v147, vcc
	v_div_scale_f32 v149, s[0:1], v147, v147, 1.0
	v_rcp_f32_e32 v154, v149
	s_nop 0
	v_fma_f32 v155, -v149, v154, 1.0
	v_fmac_f32_e32 v154, v155, v154
	v_div_scale_f32 v155, vcc, 1.0, v147, 1.0
	v_mul_f32_e32 v156, v155, v154
	v_fma_f32 v157, -v149, v156, v155
	v_fmac_f32_e32 v156, v157, v154
	v_fma_f32 v149, -v149, v156, v155
	v_div_fmas_f32 v149, v149, v154, v156
	v_div_fixup_f32 v154, v149, v147, 1.0
	v_cndmask_b32_e64 v147, 0, 1, s[64:65]
	v_add_u32_e32 v156, s60, v148
	v_cmp_ne_u32_e64 s[10:11], 1, v147
	s_andn2_b64 vcc, exec, s[64:65]
	s_cbranch_vccnz .LBB0_544
	s_mov_b64 s[12:13], -1
	s_and_b64 vcc, exec, s[16:17]
	s_cbranch_vccz .LBB0_541
	s_ashr_i32 s63, s62, 31
	v_add_u32_e32 v158, 0xfffff200, v156
	s_lshl_b64 s[0:1], s[62:63], 9
	v_ashrrev_i32_e32 v159, 31, v158
	v_lshl_add_u64 v[158:159], s[0:1], 0, v[158:159]
	s_mov_b64 s[12:13], 0

; DI float rs_of(const float* ss, int row) { return 1.0f / sqrtf(ss[row] * (1.0f / DM) + EPS); }
;     DI void operator()(AccRef acc, const Unit& u, int wr, int wc, int fr, int fq) const {
;     ...
;                     const int rl = rl0 + ai * 128 + m * 16; const float r = rs_of(ss, pm * 256 + rl);
;                     int b, s; if (smp) { b = rl >> 5; s = rl & 31; } else { b = pm >> 4; s = (pm & 15) * 256 + rl; }
;                     if (f32out) { const size_t orow = smp ? (size_t)rl : (size_t)b * 512 + (s - 3584);
.LBB0_556:
	v_add_u32_e32 v156, 16, v148
	v_add_u32_e32 v154, s49, v156
	v_ashrrev_i32_e32 v155, 31, v154
	v_lshl_add_u64 v[154:155], v[154:155], 2, s[38:39]
	v_mov_b32_e32 v147, v215
	v_fmamk_f32 v147, v147, 0x3a000000, v167
	v_cmp_gt_f32_e32 vcc, s88, v147
	v_mul_f32_e32 v149, 0x4f800000, v147
	s_nop 0
	v_cndmask_b32_e32 v147, v147, v149, vcc
	v_sqrt_f32_e32 v149, v147
	s_nop 0
	v_add_u32_e32 v154, -1, v149
	v_fma_f32 v155, -v154, v149, v147
	v_cmp_ge_f32_e64 s[14:15], 0, v155
	v_add_u32_e32 v155, 1, v149
	s_nop 0
	v_cndmask_b32_e64 v154, v149, v154, s[14:15]
	v_fma_f32 v149, -v155, v149, v147
	v_cmp_lt_f32_e64 s[14:15], 0, v149
	s_nop 1
	v_cndmask_b32_e64 v149, v154, v155, s[14:15]
	v_mul_f32_e32 v154, 0x37800000, v149
	v_cndmask_b32_e32 v149, v149, v154, vcc
	v_cmp_class_f32_e32 vcc, v147, v168
	s_nop 1
	v_cndmask_b32_e32 v147, v149, v147, vcc
	v_div_scale_f32 v149, s[0:1], v147, v147, 1.0
	v_rcp_f32_e32 v154, v149
	s_nop 0
	v_fma_f32 v155, -v149, v154, 1.0
	v_fmac_f32_e32 v154, v155, v154
	v_div_scale_f32 v155, vcc, 1.0, v147, 1.0
	v_mul_f32_e32 v157, v155, v154
	v_fma_f32 v158, -v149, v157, v155
	v_fmac_f32_e32 v157, v158, v154
	v_fma_f32 v149, -v149, v157, v155
	v_div_fmas_f32 v149, v149, v154, v157
	v_div_fixup_f32 v154, v149, v147, 1.0
	v_cndmask_b32_e64 v147, 0, 1, s[16:17]
	s_and_b64 vcc, exec, s[10:11]
	v_cmp_ne_u32_e64 s[14:15], 1, v147
	s_cbranch_vccnz .LBB0_562
	s_and_b64 vcc, exec, s[14:15]
	s_mov_b64 s[16:17], -1
	s_cbranch_vccnz .LBB0_559
	v_add_u32_e32 v147, s60, v156
	s_ashr_i32 s63, s62, 31
	v_add_u32_e32 v158, 0xfffff200, v147
	s_lshl_b64 s[0:1], s[62:63], 9
	v_ashrrev_i32_e32 v159, 31, v158
	v_lshl_add_u64 v[158:159], s[0:1], 0, v[158:159]
	s_mov_b64 s[16:17], 0

; DI float rs_of(const float* ss, int row) { return 1.0f / sqrtf(ss[row] * (1.0f / DM) + EPS); }
;     DI void operator()(AccRef acc, const Unit& u, int wr, int wc, int fr, int fq) const {
;     ...
;                     const int rl = rl0 + ai * 128 + m * 16; const float r = rs_of(ss, pm * 256 + rl);
;                     int b, s; if (smp) { b = rl >> 5; s = rl & 31; } else { b = pm >> 4; s = (pm & 15) * 256 + rl; }
;                     if (f32out) { const size_t orow = smp ? (size_t)rl : (size_t)b * 512 + (s - 3584);
.LBB0_574:
	v_add_u32_e32 v156, 32, v148
	v_add_u32_e32 v154, s49, v156
	v_ashrrev_i32_e32 v155, 31, v154
	v_lshl_add_u64 v[154:155], v[154:155], 2, s[38:39]
	v_mov_b32_e32 v149, v236
	v_fmamk_f32 v149, v149, 0x3a000000, v167
	v_mul_f32_e32 v154, 0x4f800000, v149
	v_cmp_gt_f32_e32 vcc, s88, v149
	s_nop 1
	v_cndmask_b32_e32 v149, v149, v154, vcc
	v_sqrt_f32_e32 v154, v149
	s_nop 0
	v_add_u32_e32 v155, -1, v154
	v_add_u32_e32 v157, 1, v154
	v_fma_f32 v158, -v155, v154, v149
	v_fma_f32 v159, -v157, v154, v149
	v_cmp_ge_f32_e64 s[16:17], 0, v158
	s_nop 1
	v_cndmask_b32_e64 v154, v154, v155, s[16:17]
	v_cmp_lt_f32_e64 s[16:17], 0, v159
	s_nop 1
	v_cndmask_b32_e64 v154, v154, v157, s[16:17]
	v_mul_f32_e32 v155, 0x37800000, v154
	v_cndmask_b32_e32 v154, v154, v155, vcc
	v_cmp_class_f32_e32 vcc, v149, v168
	s_nop 1
	v_cndmask_b32_e32 v149, v154, v149, vcc
	v_div_scale_f32 v154, s[0:1], v149, v149, 1.0
	v_rcp_f32_e32 v155, v154
	v_div_scale_f32 v157, vcc, 1.0, v149, 1.0
	v_fma_f32 v158, -v154, v155, 1.0
	v_fmac_f32_e32 v155, v158, v155
	v_mul_f32_e32 v158, v157, v155
	v_fma_f32 v159, -v154, v158, v157
	v_fmac_f32_e32 v158, v159, v155
	v_fma_f32 v154, -v154, v158, v157
	v_div_fmas_f32 v154, v154, v155, v158
	s_and_b64 vcc, exec, s[10:11]
	v_div_fixup_f32 v154, v154, v149, 1.0
	s_cbranch_vccnz .LBB0_581
	s_and_b64 vcc, exec, s[14:15]
	s_mov_b64 s[16:17], -1
	s_cbranch_vccnz .LBB0_577
	v_add_u32_e32 v149, s60, v156
	s_ashr_i32 s63, s62, 31
	v_add_u32_e32 v158, 0xfffff200, v149
	s_lshl_b64 s[0:1], s[62:63], 9
	v_ashrrev_i32_e32 v159, 31, v158
	v_lshl_add_u64 v[158:159], s[0:1], 0, v[158:159]
	s_mov_b64 s[16:17], 0

; DI float rs_of(const float* ss, int row) { return 1.0f / sqrtf(ss[row] * (1.0f / DM) + EPS); }
;     DI void operator()(AccRef acc, const Unit& u, int wr, int wc, int fr, int fq) const {
;     ...
;                     const int rl = rl0 + ai * 128 + m * 16; const float r = rs_of(ss, pm * 256 + rl);
;                     int b, s; if (smp) { b = rl >> 5; s = rl & 31; } else { b = pm >> 4; s = (pm & 15) * 256 + rl; }
;                     if (f32out) { const size_t orow = smp ? (size_t)rl : (size_t)b * 512 + (s - 3584);
.LBB0_592:
	s_nop 0
	v_add_u32_e32 v156, 48, v148
	v_add_u32_e32 v154, s49, v156
	v_ashrrev_i32_e32 v155, 31, v154
	v_lshl_add_u64 v[154:155], v[154:155], 2, s[38:39]
	v_mov_b32_e32 v149, v237
	v_fmamk_f32 v149, v149, 0x3a000000, v167
	v_mul_f32_e32 v154, 0x4f800000, v149
	v_cmp_gt_f32_e32 vcc, s88, v149
	s_nop 1
	v_cndmask_b32_e32 v149, v149, v154, vcc
	v_sqrt_f32_e32 v154, v149
	s_nop 0
	v_add_u32_e32 v155, -1, v154
	v_add_u32_e32 v157, 1, v154
	v_fma_f32 v158, -v155, v154, v149
	v_fma_f32 v159, -v157, v154, v149
	v_cmp_ge_f32_e64 s[16:17], 0, v158
	s_nop 1
	v_cndmask_b32_e64 v154, v154, v155, s[16:17]
	v_cmp_lt_f32_e64 s[16:17], 0, v159
	s_nop 1
	v_cndmask_b32_e64 v154, v154, v157, s[16:17]
	v_mul_f32_e32 v155, 0x37800000, v154
	v_cndmask_b32_e32 v154, v154, v155, vcc
	v_cmp_class_f32_e32 vcc, v149, v168
	s_nop 1
	v_cndmask_b32_e32 v149, v154, v149, vcc
	v_div_scale_f32 v154, s[0:1], v149, v149, 1.0
	v_rcp_f32_e32 v155, v154
	v_div_scale_f32 v157, vcc, 1.0, v149, 1.0
	v_fma_f32 v158, -v154, v155, 1.0
	v_fmac_f32_e32 v155, v158, v155
	v_mul_f32_e32 v158, v157, v155
	v_fma_f32 v159, -v154, v158, v157
	v_fmac_f32_e32 v158, v159, v155
	v_fma_f32 v154, -v154, v158, v157
	v_div_fmas_f32 v154, v154, v155, v158
	s_and_b64 vcc, exec, s[10:11]
	v_div_fixup_f32 v154, v154, v149, 1.0
	s_cbranch_vccnz .LBB0_599
	s_and_b64 vcc, exec, s[14:15]
	s_mov_b64 s[16:17], -1
	s_cbranch_vccnz .LBB0_595
	v_add_u32_e32 v149, s60, v156
	s_ashr_i32 s63, s62, 31
	v_add_u32_e32 v158, 0xfffff200, v149
	s_lshl_b64 s[0:1], s[62:63], 9
	v_ashrrev_i32_e32 v159, 31, v158
	v_lshl_add_u64 v[158:159], s[0:1], 0, v[158:159]
	s_mov_b64 s[16:17], 0

; DI float rs_of(const float* ss, int row) { return 1.0f / sqrtf(ss[row] * (1.0f / DM) + EPS); }
;     DI void operator()(AccRef acc, const Unit& u, int wr, int wc, int fr, int fq) const {
;     ...
;                     const int rl = rl0 + ai * 128 + m * 16; const float r = rs_of(ss, pm * 256 + rl);
;                     int b, s; if (smp) { b = rl >> 5; s = rl & 31; } else { b = pm >> 4; s = (pm & 15) * 256 + rl; }
;                     if (f32out) { const size_t orow = smp ? (size_t)rl : (size_t)b * 512 + (s - 3584);
.LBB0_610:
	s_nop 0
	v_add_u32_e32 v156, 0x80, v148
	v_add_u32_e32 v154, s49, v156
	v_ashrrev_i32_e32 v155, 31, v154
	v_lshl_add_u64 v[154:155], v[154:155], 2, s[38:39]
	v_mov_b32_e32 v149, v238
	v_fmamk_f32 v149, v149, 0x3a000000, v167
	v_mul_f32_e32 v154, 0x4f800000, v149
	v_cmp_gt_f32_e32 vcc, s88, v149
	s_nop 1
	v_cndmask_b32_e32 v149, v149, v154, vcc
	v_sqrt_f32_e32 v154, v149
	s_nop 0
	v_add_u32_e32 v155, -1, v154
	v_add_u32_e32 v157, 1, v154
	v_fma_f32 v158, -v155, v154, v149
	v_fma_f32 v159, -v157, v154, v149
	v_cmp_ge_f32_e64 s[16:17], 0, v158
	s_nop 1
	v_cndmask_b32_e64 v154, v154, v155, s[16:17]
	v_cmp_lt_f32_e64 s[16:17], 0, v159
	s_nop 1
	v_cndmask_b32_e64 v154, v154, v157, s[16:17]
	v_mul_f32_e32 v155, 0x37800000, v154
	v_cndmask_b32_e32 v154, v154, v155, vcc
	v_cmp_class_f32_e32 vcc, v149, v168
	s_nop 1
	v_cndmask_b32_e32 v149, v154, v149, vcc
	v_div_scale_f32 v154, s[0:1], v149, v149, 1.0
	v_rcp_f32_e32 v155, v154
	v_div_scale_f32 v157, vcc, 1.0, v149, 1.0
	v_fma_f32 v158, -v154, v155, 1.0
	v_fmac_f32_e32 v155, v158, v155
	v_mul_f32_e32 v158, v157, v155
	v_fma_f32 v159, -v154, v158, v157
	v_fmac_f32_e32 v158, v159, v155
	v_fma_f32 v154, -v154, v158, v157
	v_div_fmas_f32 v154, v154, v155, v158
	s_and_b64 vcc, exec, s[10:11]
	v_div_fixup_f32 v154, v154, v149, 1.0
	s_cbranch_vccnz .LBB0_617
	s_and_b64 vcc, exec, s[14:15]
	s_mov_b64 s[16:17], -1
	s_cbranch_vccnz .LBB0_613
	v_add_u32_e32 v149, s60, v156
	s_ashr_i32 s63, s62, 31
	v_add_u32_e32 v158, 0xfffff200, v149
	s_lshl_b64 s[0:1], s[62:63], 9
	v_ashrrev_i32_e32 v159, 31, v158
	v_lshl_add_u64 v[158:159], s[0:1], 0, v[158:159]
	s_mov_b64 s[16:17], 0

; DI float rs_of(const float* ss, int row) { return 1.0f / sqrtf(ss[row] * (1.0f / DM) + EPS); }
;     DI void operator()(AccRef acc, const Unit& u, int wr, int wc, int fr, int fq) const {
;     ...
;                     const int rl = rl0 + ai * 128 + m * 16; const float r = rs_of(ss, pm * 256 + rl);
;                     int b, s; if (smp) { b = rl >> 5; s = rl & 31; } else { b = pm >> 4; s = (pm & 15) * 256 + rl; }
;                     if (f32out) { const size_t orow = smp ? (size_t)rl : (size_t)b * 512 + (s - 3584);
.LBB0_628:
	s_nop 0
	v_add_u32_e32 v156, 0x90, v148
	v_add_u32_e32 v154, s49, v156
	v_ashrrev_i32_e32 v155, 31, v154
	v_lshl_add_u64 v[154:155], v[154:155], 2, s[38:39]
	v_mov_b32_e32 v149, v239
	v_fmamk_f32 v149, v149, 0x3a000000, v167
	v_mul_f32_e32 v154, 0x4f800000, v149
	v_cmp_gt_f32_e32 vcc, s88, v149
	s_nop 1
	v_cndmask_b32_e32 v149, v149, v154, vcc
	v_sqrt_f32_e32 v154, v149
	s_nop 0
	v_add_u32_e32 v155, -1, v154
	v_add_u32_e32 v157, 1, v154
	v_fma_f32 v158, -v155, v154, v149
	v_fma_f32 v159, -v157, v154, v149
	v_cmp_ge_f32_e64 s[16:17], 0, v158
	s_nop 1
	v_cndmask_b32_e64 v154, v154, v155, s[16:17]
	v_cmp_lt_f32_e64 s[16:17], 0, v159
	s_nop 1
	v_cndmask_b32_e64 v154, v154, v157, s[16:17]
	v_mul_f32_e32 v155, 0x37800000, v154
	v_cndmask_b32_e32 v154, v154, v155, vcc
	v_cmp_class_f32_e32 vcc, v149, v168
	s_nop 1
	v_cndmask_b32_e32 v149, v154, v149, vcc
	v_div_scale_f32 v154, s[0:1], v149, v149, 1.0
	v_rcp_f32_e32 v155, v154
	v_div_scale_f32 v157, vcc, 1.0, v149, 1.0
	v_fma_f32 v158, -v154, v155, 1.0
	v_fmac_f32_e32 v155, v158, v155
	v_mul_f32_e32 v158, v157, v155
	v_fma_f32 v159, -v154, v158, v157
	v_fmac_f32_e32 v158, v159, v155
	v_fma_f32 v154, -v154, v158, v157
	v_div_fmas_f32 v154, v154, v155, v158
	s_and_b64 vcc, exec, s[10:11]
	v_div_fixup_f32 v154, v154, v149, 1.0
	s_cbranch_vccnz .LBB0_635
	s_and_b64 vcc, exec, s[14:15]
	s_mov_b64 s[16:17], -1
	s_cbranch_vccnz .LBB0_631
	v_add_u32_e32 v149, s60, v156
	s_ashr_i32 s63, s62, 31
	v_add_u32_e32 v158, 0xfffff200, v149
	s_lshl_b64 s[0:1], s[62:63], 9
	v_ashrrev_i32_e32 v159, 31, v158
	v_lshl_add_u64 v[158:159], s[0:1], 0, v[158:159]
	s_mov_b64 s[16:17], 0

; DI float rs_of(const float* ss, int row) { return 1.0f / sqrtf(ss[row] * (1.0f / DM) + EPS); }
;     DI void operator()(AccRef acc, const Unit& u, int wr, int wc, int fr, int fq) const {
;     ...
;                     const int rl = rl0 + ai * 128 + m * 16; const float r = rs_of(ss, pm * 256 + rl);
;                     int b, s; if (smp) { b = rl >> 5; s = rl & 31; } else { b = pm >> 4; s = (pm & 15) * 256 + rl; }
;                     if (f32out) { const size_t orow = smp ? (size_t)rl : (size_t)b * 512 + (s - 3584);
.LBB0_646:
	s_nop 0
	v_add_u32_e32 v156, 0xa0, v148
	v_add_u32_e32 v154, s49, v156
	v_ashrrev_i32_e32 v155, 31, v154
	v_lshl_add_u64 v[154:155], v[154:155], 2, s[38:39]
	v_mov_b32_e32 v149, v232
	v_fmamk_f32 v149, v149, 0x3a000000, v167
	v_mul_f32_e32 v154, 0x4f800000, v149
	v_cmp_gt_f32_e32 vcc, s88, v149
	s_nop 1
	v_cndmask_b32_e32 v149, v149, v154, vcc
	v_sqrt_f32_e32 v154, v149
	s_nop 0
	v_add_u32_e32 v155, -1, v154
	v_add_u32_e32 v157, 1, v154
	v_fma_f32 v158, -v155, v154, v149
	v_fma_f32 v159, -v157, v154, v149
	v_cmp_ge_f32_e64 s[16:17], 0, v158
	s_nop 1
	v_cndmask_b32_e64 v154, v154, v155, s[16:17]
	v_cmp_lt_f32_e64 s[16:17], 0, v159
	s_nop 1
	v_cndmask_b32_e64 v154, v154, v157, s[16:17]
	v_mul_f32_e32 v155, 0x37800000, v154
	v_cndmask_b32_e32 v154, v154, v155, vcc
	v_cmp_class_f32_e32 vcc, v149, v168
	s_nop 1
	v_cndmask_b32_e32 v149, v154, v149, vcc
	v_div_scale_f32 v154, s[0:1], v149, v149, 1.0
	v_rcp_f32_e32 v155, v154
	v_div_scale_f32 v157, vcc, 1.0, v149, 1.0
	v_fma_f32 v158, -v154, v155, 1.0
	v_fmac_f32_e32 v155, v158, v155
	v_mul_f32_e32 v158, v157, v155
	v_fma_f32 v159, -v154, v158, v157
	v_fmac_f32_e32 v158, v159, v155
	v_fma_f32 v154, -v154, v158, v157
	v_div_fmas_f32 v154, v154, v155, v158
	s_and_b64 vcc, exec, s[10:11]
	v_div_fixup_f32 v154, v154, v149, 1.0
	s_cbranch_vccnz .LBB0_653
	s_and_b64 vcc, exec, s[14:15]
	s_mov_b64 s[16:17], -1
	s_cbranch_vccnz .LBB0_649
	v_add_u32_e32 v149, s60, v156
	s_ashr_i32 s63, s62, 31
	v_add_u32_e32 v158, 0xfffff200, v149
	s_lshl_b64 s[0:1], s[62:63], 9
	v_ashrrev_i32_e32 v159, 31, v158
	v_lshl_add_u64 v[158:159], s[0:1], 0, v[158:159]
	s_mov_b64 s[16:17], 0

; DI float rs_of(const float* ss, int row) { return 1.0f / sqrtf(ss[row] * (1.0f / DM) + EPS); }
;     DI void operator()(AccRef acc, const Unit& u, int wr, int wc, int fr, int fq) const {
;     ...
;                     const int rl = rl0 + ai * 128 + m * 16; const float r = rs_of(ss, pm * 256 + rl);
;                     int b, s; if (smp) { b = rl >> 5; s = rl & 31; } else { b = pm >> 4; s = (pm & 15) * 256 + rl; }
;                     if (f32out) { const size_t orow = smp ? (size_t)rl : (size_t)b * 512 + (s - 3584);
.LBB0_664:
	s_nop 0
	v_add_u32_e32 v156, 0xb0, v148
	v_add_u32_e32 v154, s49, v156
	v_ashrrev_i32_e32 v155, 31, v154
	v_lshl_add_u64 v[154:155], v[154:155], 2, s[38:39]
	v_mov_b32_e32 v137, v233
	v_fmamk_f32 v137, v137, 0x3a000000, v167
	v_mul_f32_e32 v149, 0x4f800000, v137
	v_cmp_gt_f32_e32 vcc, s88, v137
	s_nop 1
	v_cndmask_b32_e32 v137, v137, v149, vcc
	v_sqrt_f32_e32 v149, v137
	s_nop 0
	v_add_u32_e32 v154, -1, v149
	v_add_u32_e32 v155, 1, v149
	v_fma_f32 v157, -v154, v149, v137
	v_fma_f32 v158, -v155, v149, v137
	v_cmp_ge_f32_e64 s[16:17], 0, v157
	s_nop 1
	v_cndmask_b32_e64 v149, v149, v154, s[16:17]
	v_cmp_lt_f32_e64 s[16:17], 0, v158
	s_nop 1
	v_cndmask_b32_e64 v149, v149, v155, s[16:17]
	v_mul_f32_e32 v154, 0x37800000, v149
	v_cndmask_b32_e32 v149, v149, v154, vcc
	v_cmp_class_f32_e32 vcc, v137, v168
	s_nop 1
	v_cndmask_b32_e32 v137, v149, v137, vcc
	v_div_scale_f32 v149, s[0:1], v137, v137, 1.0
	v_rcp_f32_e32 v154, v149
	v_div_scale_f32 v155, vcc, 1.0, v137, 1.0
	v_fma_f32 v157, -v149, v154, 1.0
	v_fmac_f32_e32 v154, v157, v154
	v_mul_f32_e32 v157, v155, v154
	v_fma_f32 v158, -v149, v157, v155
	v_fmac_f32_e32 v157, v158, v154
	v_fma_f32 v149, -v149, v157, v155
	v_div_fmas_f32 v149, v149, v154, v157
	s_and_b64 vcc, exec, s[10:11]
	v_div_fixup_f32 v154, v149, v137, 1.0
	s_cbranch_vccnz .LBB0_671
	s_and_b64 vcc, exec, s[14:15]
	s_mov_b64 s[10:11], -1
	s_cbranch_vccnz .LBB0_667
	v_add_u32_e32 v137, s60, v156
	s_ashr_i32 s63, s62, 31
	v_add_u32_e32 v158, 0xfffff200, v137
	s_lshl_b64 s[0:1], s[62:63], 9
	v_ashrrev_i32_e32 v159, 31, v158
	v_lshl_add_u64 v[158:159], s[0:1], 0, v[158:159]
	s_mov_b64 s[10:11], 0
